# in-proj: next-tile global loads issued before the barriers (rotated loop), PEER-table conversion loads issued at tile start; attention K/V prefetch via scalar-base loads
# speedup vs baseline: 1.0422x; 1.0047x over previous
; __device__ __forceinline__ f32x4 mfma16(bf16x8 a, bf16x8 b, f32x4 c) { return __builtin_amdgcn_mfma_f32_16x16x32_bf16(a, b, c, 0, 0, 0); }
; template <bool PF2>
; __device__ __forceinline__ void gemm_mainloop_t(const bf16_t* __restrict__ A, int lda, const bf16_t* __restrict__ Bt, int ldb, int K,
;                                                 bf16_t* smem, f32x4 (&acc)[4][4], const int tid) {
;     ...
;   auto gload = [&](int set, int kt) {
;     const int k0 = kt << 6;
; #pragma unroll
;     for (int i = 0; i < 4; ++i) { ra[set][i] = *(const u32x4*)(ag + (size_t)(32 * i) * lda + k0); rb[set][i] = *(const u32x4*)(bg + (size_t)(32 * i) * ldb + k0); }
;   };
;   auto sstore = [&](int set, int st) {
;     bf16_t* ds = smem + st * 2 * GSTAGE;
; #pragma unroll
;     for (int i = 0; i < 4; ++i) { *(u32x4*)(ds + (lr + 32 * i) * GS + lcs) = ra[set][i]; *(u32x4*)(ds + GSTAGE + (lr + 32 * i) * GS + lcs) = rb[set][i]; }
;   };
;   auto compute = [&](int st) {
;     const bf16_t* as = smem + st * 2 * GSTAGE;
;     const bf16_t* bs = as + GSTAGE;
; #pragma unroll
;     for (int ks = 0; ks < 2; ++ks) {
;       bf16x8 af[4], bfr[4];
; #pragma unroll
;       for (int mi = 0; mi < 4; ++mi) af[mi] = *(const bf16x8*)(as + (wm * 64 + mi * 16 + fr) * GS + (((ks * 4 + fq) ^ (fr & 7)) * 8));
; #pragma unroll
;       for (int ni = 0; ni < 4; ++ni) bfr[ni] = *(const bf16x8*)(bs + (wn * 64 + ni * 16 + fr) * GS + (((ks * 4 + fq) ^ (fr & 7)) * 8));
; #pragma unroll
;       for (int mi = 0; mi < 4; ++mi)
; #pragma unroll
;         for (int ni = 0; ni < 4; ++ni) acc[mi][ni] = mfma16(bfr[ni], af[mi], acc[mi][ni]);
;     }
;   };
;   if (PF2) {
;     gload(0, 0);
;     gload(1, 1);
;     sstore(0, 0);
;     lds_barrier();
; __device__ __forceinline__ void peer_convert_chunk(const Params& p, int l, size_t i) {
;   const size_t base = (size_t)l * 16384 * 1024 + i * 16;
;   u32x4 ou, ov;
; #pragma unroll
;   for (int c = 0; c < 4; ++c) {
;     const f32x4 a = *(const f32x4*)(p.peer_u + base + c * 4) * 256.f;
;     int r = 0; r = __builtin_amdgcn_cvt_pk_fp8_f32(a[0], a[1], r, false); r = __builtin_amdgcn_cvt_pk_fp8_f32(a[2], a[3], r, true); ou[c] = (unsigned)r;
;     const f32x4 d = *(const f32x4*)(p.peer_v + base + c * 4) * 64.f;
;     int q = 0; q = __builtin_amdgcn_cvt_pk_fp8_f32(d[0], d[1], q, false); q = __builtin_amdgcn_cvt_pk_fp8_f32(d[2], d[3], q, true); ov[c] = (unsigned)q;
.LBB0_177:
	s_mul_i32 s0, s16, s52
	v_readlane_b32 s2, v252, 0
	s_mul_hi_u32 s1, s16, s52
	s_add_u32 s0, s0, s2
	s_addc_u32 s1, s1, 0
	s_lshl_b64 s[0:1], s[0:1], 8
	v_lshl_add_u64 v[244:245], s[0:1], 0, v[130:131]
	s_mov_b64 s[0:1], 0x100000
	v_cmp_gt_u64_e32 vcc, s[0:1], v[244:245]
	s_and_saveexec_b64 s[0:1], vcc
	s_cbranch_execz .Lpeer_pf_done
	v_readlane_b32 s2, v254, 38
	v_readlane_b32 s3, v254, 39
	v_lshlrev_b64 v[244:245], 4, v[244:245]
	s_nop 1
	v_or_b32_e32 v244, s2, v244
	v_or_b32_e32 v245, s3, v245
	v_lshlrev_b64 v[244:245], 2, v[244:245]
	v_readlane_b32 s2, v253, 49
	v_readlane_b32 s3, v253, 50
	s_nop 1
	v_lshl_add_u64 v[246:247], s[2:3], 0, v[244:245]
	v_readlane_b32 s2, v253, 57
	v_readlane_b32 s3, v253, 58
	s_nop 1
	v_lshl_add_u64 v[244:245], s[2:3], 0, v[244:245]
	global_load_dwordx4 v[212:215], v[244:245], off offset:48
	global_load_dwordx4 v[216:219], v[244:245], off offset:32
	global_load_dwordx4 v[220:223], v[244:245], off offset:16
	global_load_dwordx4 v[224:227], v[244:245], off
	global_load_dwordx4 v[228:231], v[246:247], off offset:48
	global_load_dwordx4 v[232:235], v[246:247], off offset:32
	global_load_dwordx4 v[236:239], v[246:247], off offset:16
	global_load_dwordx4 v[240:243], v[246:247], off
.Lpeer_pf_done:
	s_or_b64 exec, exec, s[0:1]
	s_ashr_i32 s15, s14, 31
	s_lshl_b64 s[0:1], s[14:15], 18
	s_ashr_i32 s13, s12, 31
	v_lshl_add_u64 v[142:143], v[134:135], 0, s[0:1]
	s_lshl_b64 s[2:3], s[12:13], 18
	v_add_co_u32_e32 v2, vcc, 0x10000, v142
	v_lshl_add_u64 v[144:145], v[132:133], 0, s[2:3]
	s_nop 0
	v_addc_co_u32_e32 v3, vcc, 0, v143, vcc
	v_add_co_u32_e32 v4, vcc, 0x10000, v144
	global_load_dwordx4 v[66:69], v[142:143], off
	global_load_dwordx4 v[70:73], v[144:145], off
	v_addc_co_u32_e32 v5, vcc, 0, v145, vcc
	v_add_co_u32_e32 v6, vcc, 0x20000, v142
	global_load_dwordx4 v[74:77], v[2:3], off
	s_nop 0
	v_addc_co_u32_e32 v7, vcc, 0, v143, vcc
	v_add_co_u32_e32 v8, vcc, 0x20000, v144
	global_load_dwordx4 v[78:81], v[4:5], off
	s_nop 0
	v_addc_co_u32_e32 v9, vcc, 0, v145, vcc
	v_add_co_u32_e32 v10, vcc, 0x30000, v142
	global_load_dwordx4 v[82:85], v[6:7], off
	s_nop 0
	v_addc_co_u32_e32 v11, vcc, 0, v143, vcc
	v_add_co_u32_e32 v12, vcc, 0x30000, v144
	global_load_dwordx4 v[86:89], v[8:9], off
	s_nop 0
	v_addc_co_u32_e32 v13, vcc, 0, v145, vcc
	global_load_dwordx4 v[90:93], v[10:11], off
	global_load_dwordx4 v[94:97], v[12:13], off
	global_load_dwordx4 v[34:37], v[142:143], off offset:128
	global_load_dwordx4 v[38:41], v[144:145], off offset:128
	global_load_dwordx4 v[42:45], v[2:3], off offset:128
	global_load_dwordx4 v[46:49], v[4:5], off offset:128
	global_load_dwordx4 v[50:53], v[6:7], off offset:128
	global_load_dwordx4 v[58:61], v[8:9], off offset:128
	global_load_dwordx4 v[54:57], v[10:11], off offset:128
	global_load_dwordx4 v[62:65], v[12:13], off offset:128
	s_mov_b64 s[2:3], 0x10000
	v_lshl_add_u64 v[146:147], v[142:143], 0, s[2:3]
	v_lshl_add_u64 v[148:149], v[144:145], 0, s[2:3]
	s_mov_b64 s[2:3], 0x20000
	v_mov_b32_e32 v14, 0
	v_lshl_add_u64 v[150:151], v[142:143], 0, s[2:3]
	v_lshl_add_u64 v[152:153], v[144:145], 0, s[2:3]
	s_mov_b64 s[2:3], 0x30000
	s_mov_b32 s0, -2
	v_mov_b32_e32 v15, v14
	v_mov_b32_e32 v16, v14
	v_mov_b32_e32 v17, v14
	v_mov_b32_e32 v2, v14
	v_mov_b32_e32 v3, v14
	v_mov_b32_e32 v4, v14
	v_mov_b32_e32 v5, v14
	v_mov_b32_e32 v6, v14
	v_mov_b32_e32 v7, v14
	v_mov_b32_e32 v8, v14
	v_mov_b32_e32 v9, v14
	v_mov_b32_e32 v10, v14
	v_mov_b32_e32 v11, v14
	v_mov_b32_e32 v12, v14
	v_mov_b32_e32 v13, v14
	s_waitcnt vmcnt(0)
	v_mov_b32_e32 v18, v14
	v_mov_b32_e32 v19, v14
	v_mov_b32_e32 v20, v14
	v_mov_b32_e32 v21, v14
	v_mov_b32_e32 v22, v14
	v_mov_b32_e32 v23, v14
	v_mov_b32_e32 v24, v14
	v_mov_b32_e32 v25, v14
	v_mov_b32_e32 v26, v14
	v_mov_b32_e32 v27, v14
	v_mov_b32_e32 v28, v14
	v_mov_b32_e32 v29, v14
	v_mov_b32_e32 v30, v14
	v_mov_b32_e32 v31, v14
	v_mov_b32_e32 v32, v14
	v_mov_b32_e32 v33, v14
	v_lshl_add_u64 v[154:155], v[142:143], 0, s[2:3]
	v_lshl_add_u64 v[156:157], v[144:145], 0, s[2:3]
	s_waitcnt vmcnt(0)
	ds_write_b128 v160, v[66:69]
	ds_write_b128 v160, v[70:73] offset:16384
	ds_write_b128 v160, v[74:77] offset:4096
	ds_write_b128 v160, v[78:81] offset:20480
	ds_write_b128 v160, v[82:85] offset:8192
	ds_write_b128 v160, v[86:89] offset:24576
	ds_write_b128 v160, v[90:93] offset:12288
	ds_write_b128 v160, v[94:97] offset:28672
	s_waitcnt lgkmcnt(0)
	s_barrier
	v_mov_b32_e32 v66, v14
	v_mov_b32_e32 v67, v14
	v_mov_b32_e32 v68, v14
	v_mov_b32_e32 v69, v14
	v_mov_b32_e32 v74, v14
	v_mov_b32_e32 v75, v14
	v_mov_b32_e32 v76, v14
	v_mov_b32_e32 v77, v14
	v_mov_b32_e32 v82, v14
	v_mov_b32_e32 v83, v14
	v_mov_b32_e32 v84, v14
	v_mov_b32_e32 v85, v14
	v_mov_b32_e32 v94, v14
	v_mov_b32_e32 v95, v14
	v_mov_b32_e32 v96, v14
	v_mov_b32_e32 v97, v14
	v_mov_b32_e32 v70, v14
	v_mov_b32_e32 v71, v14
	v_mov_b32_e32 v72, v14
	v_mov_b32_e32 v73, v14
	v_mov_b32_e32 v78, v14
	v_mov_b32_e32 v79, v14
	v_mov_b32_e32 v80, v14
	v_mov_b32_e32 v81, v14
	v_mov_b32_e32 v86, v14
	v_mov_b32_e32 v87, v14
	v_mov_b32_e32 v88, v14
	v_mov_b32_e32 v89, v14
	v_mov_b32_e32 v90, v14
	v_mov_b32_e32 v91, v14
	v_mov_b32_e32 v92, v14
	v_mov_b32_e32 v93, v14

; __device__ __forceinline__ f32x4 mfma16(bf16x8 a, bf16x8 b, f32x4 c) { return __builtin_amdgcn_mfma_f32_16x16x32_bf16(a, b, c, 0, 0, 0); }
; __device__ __forceinline__ void lds_barrier() { asm volatile("s_waitcnt lgkmcnt(0)\n\ts_barrier" ::: "memory"); }
; template <bool PF2>
; __device__ __forceinline__ void gemm_mainloop_t(const bf16_t* __restrict__ A, int lda, const bf16_t* __restrict__ Bt, int ldb, int K,
;                                                 bf16_t* smem, f32x4 (&acc)[4][4], const int tid) {
;     ...
;   auto compute = [&](int st) {
;     const bf16_t* as = smem + st * 2 * GSTAGE;
;     const bf16_t* bs = as + GSTAGE;
; #pragma unroll
;     for (int ks = 0; ks < 2; ++ks) {
;       bf16x8 af[4], bfr[4];
; #pragma unroll
;       for (int mi = 0; mi < 4; ++mi) af[mi] = *(const bf16x8*)(as + (wm * 64 + mi * 16 + fr) * GS + (((ks * 4 + fq) ^ (fr & 7)) * 8));
; #pragma unroll
;       for (int ni = 0; ni < 4; ++ni) bfr[ni] = *(const bf16x8*)(bs + (wn * 64 + ni * 16 + fr) * GS + (((ks * 4 + fq) ^ (fr & 7)) * 8));
; #pragma unroll
;       for (int mi = 0; mi < 4; ++mi)
; #pragma unroll
;         for (int ni = 0; ni < 4; ++ni) acc[mi][ni] = mfma16(bfr[ni], af[mi], acc[mi][ni]);
;     }
;   };
;   if (PF2) {
;     gload(0, 0);
;     gload(1, 1);
;     sstore(0, 0);
;     lds_barrier();
;     for (int kt = 0; kt < nk; kt += 2) {
;       gload(0, min(kt + 2, nk - 1));
;       __builtin_amdgcn_sched_barrier(0);
;       compute(0);
;       sstore(1, 1);
;       lds_barrier();
;       gload(1, min(kt + 3, nk - 1));
;       __builtin_amdgcn_sched_barrier(0);
;       compute(1);
.Lrot178_body:
	ds_read_b128 v[168:171], v162 offset:16384
	ds_read_b128 v[172:175], v162 offset:18432
	ds_read_b128 v[176:179], v161
	ds_read_b128 v[180:183], v161 offset:2048
	ds_read_b128 v[184:187], v162 offset:20480
	ds_read_b128 v[202:205], v162 offset:22528
	s_min_u32 s1, s0, 12
	s_waitcnt lgkmcnt(3)
	v_mfma_f32_16x16x32_bf16 v[90:93], v[168:171], v[176:179], v[90:93]
	s_lshl_b32 s74, s1, 7
	v_mfma_f32_16x16x32_bf16 v[86:89], v[172:175], v[176:179], v[86:89]
	s_waitcnt lgkmcnt(1)
	v_mfma_f32_16x16x32_bf16 v[78:81], v[184:187], v[176:179], v[78:81]
	s_waitcnt lgkmcnt(0)
	v_mfma_f32_16x16x32_bf16 v[70:73], v[202:205], v[176:179], v[70:73]
	v_mfma_f32_16x16x32_bf16 v[94:97], v[168:171], v[180:183], v[94:97]
	v_mfma_f32_16x16x32_bf16 v[82:85], v[172:175], v[180:183], v[82:85]
	v_mfma_f32_16x16x32_bf16 v[74:77], v[184:187], v[180:183], v[74:77]
	v_mfma_f32_16x16x32_bf16 v[66:69], v[202:205], v[180:183], v[66:69]
	ds_read_b128 v[176:179], v161 offset:4096
	ds_read_b128 v[180:183], v161 offset:6144
	s_waitcnt lgkmcnt(1)
	v_mfma_f32_16x16x32_bf16 v[30:33], v[168:171], v[176:179], v[30:33]
	v_mfma_f32_16x16x32_bf16 v[26:29], v[172:175], v[176:179], v[26:29]
	v_mfma_f32_16x16x32_bf16 v[22:25], v[184:187], v[176:179], v[22:25]
	v_mfma_f32_16x16x32_bf16 v[18:21], v[202:205], v[176:179], v[18:21]
	s_waitcnt lgkmcnt(0)
	v_mfma_f32_16x16x32_bf16 v[10:13], v[168:171], v[180:183], v[10:13]
	v_mfma_f32_16x16x32_bf16 v[6:9], v[172:175], v[180:183], v[6:9]
	ds_read_b128 v[168:171], v164 offset:16384
	ds_read_b128 v[172:175], v164 offset:18432
	v_mfma_f32_16x16x32_bf16 v[2:5], v[184:187], v[180:183], v[2:5]
	v_mfma_f32_16x16x32_bf16 v[14:17], v[202:205], v[180:183], v[14:17]
	ds_read_b128 v[176:179], v163
	ds_read_b128 v[180:183], v163 offset:2048
	ds_read_b128 v[184:187], v164 offset:20480
	ds_read_b128 v[202:205], v164 offset:22528
	s_waitcnt lgkmcnt(3)
	v_mfma_f32_16x16x32_bf16 v[90:93], v[168:171], v[176:179], v[90:93]
	v_mfma_f32_16x16x32_bf16 v[86:89], v[172:175], v[176:179], v[86:89]
	s_waitcnt lgkmcnt(1)
	v_mfma_f32_16x16x32_bf16 v[78:81], v[184:187], v[176:179], v[78:81]
	s_waitcnt lgkmcnt(0)
	v_mfma_f32_16x16x32_bf16 v[70:73], v[202:205], v[176:179], v[70:73]
	ds_read_b128 v[176:179], v163 offset:4096
	ds_read_b128 v[206:209], v163 offset:6144
	s_waitcnt vmcnt(15)
	ds_write_b128 v160, v[34:37] offset:32768
	s_waitcnt vmcnt(14)
	ds_write_b128 v160, v[38:41] offset:49152
	s_waitcnt vmcnt(13)
	ds_write_b128 v160, v[42:45] offset:36864
	s_waitcnt vmcnt(12)
	ds_write_b128 v160, v[46:49] offset:53248
	s_waitcnt vmcnt(11)
	ds_write_b128 v160, v[50:53] offset:40960
	s_waitcnt vmcnt(10)
	ds_write_b128 v160, v[58:61] offset:57344
	s_waitcnt vmcnt(9)
	ds_write_b128 v160, v[54:57] offset:45056
	s_waitcnt vmcnt(8)
	ds_write_b128 v160, v[62:65] offset:61440
	v_lshl_add_u64 v[34:35], v[142:143], 0, s[74:75]
	v_lshl_add_u64 v[38:39], v[144:145], 0, s[74:75]
	s_addk_i32 s74, 0x180
	v_lshl_add_u64 v[42:43], v[146:147], 0, s[74:75]
	v_lshl_add_u64 v[46:47], v[148:149], 0, s[74:75]
	v_lshl_add_u64 v[50:51], v[150:151], 0, s[74:75]
	v_lshl_add_u64 v[54:55], v[152:153], 0, s[74:75]
	v_lshl_add_u64 v[56:57], v[154:155], 0, s[74:75]
	global_load_dwordx4 v[34:37], v[34:35], off offset:384
	v_lshl_add_u64 v[62:63], v[156:157], 0, s[74:75]
	global_load_dwordx4 v[38:41], v[38:39], off offset:384
	global_load_dwordx4 v[42:45], v[42:43], off
	global_load_dwordx4 v[46:49], v[46:47], off
	global_load_dwordx4 v[50:53], v[50:51], off
	global_load_dwordx4 v[58:61], v[54:55], off
	global_load_dwordx4 v[54:57], v[56:57], off
	global_load_dwordx4 v[62:65], v[62:63], off
	s_waitcnt lgkmcnt(0)
	s_barrier
	v_mfma_f32_16x16x32_bf16 v[94:97], v[168:171], v[180:183], v[94:97]
	v_mfma_f32_16x16x32_bf16 v[82:85], v[172:175], v[180:183], v[82:85]
	v_mfma_f32_16x16x32_bf16 v[74:77], v[184:187], v[180:183], v[74:77]
	v_mfma_f32_16x16x32_bf16 v[66:69], v[202:205], v[180:183], v[66:69]
	s_waitcnt lgkmcnt(9)
	v_mfma_f32_16x16x32_bf16 v[30:33], v[168:171], v[176:179], v[30:33]
	v_mfma_f32_16x16x32_bf16 v[26:29], v[172:175], v[176:179], v[26:29]
	v_mfma_f32_16x16x32_bf16 v[22:25], v[184:187], v[176:179], v[22:25]
	v_mfma_f32_16x16x32_bf16 v[18:21], v[202:205], v[176:179], v[18:21]
	s_waitcnt lgkmcnt(8)
	v_mfma_f32_16x16x32_bf16 v[10:13], v[168:171], v[206:209], v[10:13]
	v_mfma_f32_16x16x32_bf16 v[6:9], v[172:175], v[206:209], v[6:9]
	v_mfma_f32_16x16x32_bf16 v[2:5], v[184:187], v[206:209], v[2:5]
	v_mfma_f32_16x16x32_bf16 v[14:17], v[202:205], v[206:209], v[14:17]
	ds_read_b128 v[168:171], v162 offset:49152
	ds_read_b128 v[172:175], v161 offset:32768
	ds_read_b128 v[176:179], v162 offset:51200
	ds_read_b128 v[180:183], v162 offset:53248
	ds_read_b128 v[184:187], v162 offset:55296
	s_cmp_lt_u32 s0, 14
	s_waitcnt lgkmcnt(3)
	v_mfma_f32_16x16x32_bf16 v[90:93], v[168:171], v[172:175], v[90:93]
	s_waitcnt lgkmcnt(2)
	v_mfma_f32_16x16x32_bf16 v[86:89], v[176:179], v[172:175], v[86:89]
	s_waitcnt lgkmcnt(1)
	v_mfma_f32_16x16x32_bf16 v[78:81], v[180:183], v[172:175], v[78:81]
	s_waitcnt lgkmcnt(0)
	v_mfma_f32_16x16x32_bf16 v[70:73], v[184:187], v[172:175], v[70:73]
	ds_read_b128 v[172:175], v161 offset:34816
	s_waitcnt lgkmcnt(0)
	v_mfma_f32_16x16x32_bf16 v[94:97], v[168:171], v[172:175], v[94:97]
	v_mfma_f32_16x16x32_bf16 v[82:85], v[176:179], v[172:175], v[82:85]
	v_mfma_f32_16x16x32_bf16 v[74:77], v[180:183], v[172:175], v[74:77]
	v_mfma_f32_16x16x32_bf16 v[66:69], v[184:187], v[172:175], v[66:69]
	ds_read_b128 v[172:175], v161 offset:36864
	s_waitcnt lgkmcnt(0)
; __device__ __forceinline__ void lds_barrier() { asm volatile("s_waitcnt lgkmcnt(0)\n\ts_barrier" ::: "memory"); }
; template <bool PF2>
; __device__ __forceinline__ void gemm_mainloop_t(const bf16_t* __restrict__ A, int lda, const bf16_t* __restrict__ Bt, int ldb, int K,
;                                                 bf16_t* smem, f32x4 (&acc)[4][4], const int tid) {
;     ...
;     for (int kt = 0; kt < nk; kt += 2) {
;       gload(0, min(kt + 2, nk - 1));
;       __builtin_amdgcn_sched_barrier(0);
;       compute(0);
;       sstore(1, 1);
;       lds_barrier();
;       gload(1, min(kt + 3, nk - 1));
;       __builtin_amdgcn_sched_barrier(0);
;       compute(1);
;       sstore(0, 0);
;       lds_barrier();
;     }
; __device__ void phase_inproj(const Params& p, int l, unsigned char* smem) {
;     ...
;     const int rowb = mt * 128 + wm * 64 + fr;
;     const int colb = ct * 128 + wn * 64 + fq * 4;
; #pragma unroll
;     for (int mi = 0; mi < 4; ++mi) {
;       const f32x4 s0 = *(const f32x4*)(p.ssqn + (rowb + mi * 16) * 8), s1 = *(const f32x4*)(p.ssqn + (rowb + mi * 16) * 8 + 4);
;       const float rstd = rsqrtf(((s0[0] + s0[1]) + (s0[2] + s0[3]) + (s1[0] + s1[1]) + (s1[2] + s1[3])) * (1.f / 1024.f) + 1e-6f);
; #pragma unroll
;       for (int ni = 0; ni < 4; ++ni) acc[mi][ni] *= rstd;
	v_mfma_f32_16x16x32_bf16 v[30:33], v[168:171], v[172:175], v[30:33]
	v_mfma_f32_16x16x32_bf16 v[26:29], v[176:179], v[172:175], v[26:29]
	v_mfma_f32_16x16x32_bf16 v[22:25], v[180:183], v[172:175], v[22:25]
	v_mfma_f32_16x16x32_bf16 v[18:21], v[184:187], v[172:175], v[18:21]
	ds_read_b128 v[172:175], v161 offset:38912
	s_waitcnt lgkmcnt(0)
	v_mfma_f32_16x16x32_bf16 v[10:13], v[168:171], v[172:175], v[10:13]
	ds_read_b128 v[168:171], v164 offset:49152
	v_mfma_f32_16x16x32_bf16 v[6:9], v[176:179], v[172:175], v[6:9]
	ds_read_b128 v[176:179], v164 offset:51200
	v_mfma_f32_16x16x32_bf16 v[2:5], v[180:183], v[172:175], v[2:5]
	ds_read_b128 v[180:183], v164 offset:53248
	v_mfma_f32_16x16x32_bf16 v[14:17], v[184:187], v[172:175], v[14:17]
	ds_read_b128 v[184:187], v164 offset:55296
	ds_read_b128 v[172:175], v163 offset:32768
	s_waitcnt lgkmcnt(0)
	v_mfma_f32_16x16x32_bf16 v[90:93], v[168:171], v[172:175], v[90:93]
	v_mfma_f32_16x16x32_bf16 v[86:89], v[176:179], v[172:175], v[86:89]
	v_mfma_f32_16x16x32_bf16 v[78:81], v[180:183], v[172:175], v[78:81]
	v_mfma_f32_16x16x32_bf16 v[70:73], v[184:187], v[172:175], v[70:73]
	ds_read_b128 v[172:175], v163 offset:34816
	s_waitcnt lgkmcnt(0)
	v_mfma_f32_16x16x32_bf16 v[94:97], v[168:171], v[172:175], v[94:97]
	v_mfma_f32_16x16x32_bf16 v[82:85], v[176:179], v[172:175], v[82:85]
	v_mfma_f32_16x16x32_bf16 v[74:77], v[180:183], v[172:175], v[74:77]
	v_mfma_f32_16x16x32_bf16 v[66:69], v[184:187], v[172:175], v[66:69]
	ds_read_b128 v[172:175], v163 offset:36864
	s_waitcnt lgkmcnt(0)
	v_mfma_f32_16x16x32_bf16 v[30:33], v[168:171], v[172:175], v[30:33]
	v_mfma_f32_16x16x32_bf16 v[26:29], v[176:179], v[172:175], v[26:29]
	v_mfma_f32_16x16x32_bf16 v[22:25], v[180:183], v[172:175], v[22:25]
	v_mfma_f32_16x16x32_bf16 v[18:21], v[184:187], v[172:175], v[18:21]
	ds_read_b128 v[172:175], v163 offset:38912
	s_waitcnt vmcnt(15)
	ds_write_b128 v160, v[98:101]
	s_waitcnt vmcnt(14)
	ds_write_b128 v160, v[102:105] offset:16384
	s_waitcnt vmcnt(13)
	ds_write_b128 v160, v[106:109] offset:4096
	s_waitcnt vmcnt(12)
	ds_write_b128 v160, v[110:113] offset:20480
	s_waitcnt lgkmcnt(4)
	v_mfma_f32_16x16x32_bf16 v[10:13], v[168:171], v[172:175], v[10:13]
	s_waitcnt vmcnt(11)
	ds_write_b128 v160, v[114:117] offset:8192
	s_waitcnt vmcnt(10)
	ds_write_b128 v160, v[118:121] offset:24576
	s_waitcnt vmcnt(9)
	ds_write_b128 v160, v[122:125] offset:12288
	s_waitcnt vmcnt(8)
	ds_write_b128 v160, v[126:129] offset:28672
	s_cbranch_scc0 .Lrot178_last
	s_add_i32 s1, s0, 4
	s_min_u32 s1, s1, 15
	s_lshl_b32 s74, s1, 7
	v_lshl_add_u64 v[98:99], v[142:143], 0, s[74:75]
	v_lshl_add_u64 v[102:103], v[144:145], 0, s[74:75]
	v_lshl_add_u64 v[106:107], v[146:147], 0, s[74:75]
	v_lshl_add_u64 v[110:111], v[148:149], 0, s[74:75]
	v_lshl_add_u64 v[114:115], v[150:151], 0, s[74:75]
	v_lshl_add_u64 v[118:119], v[152:153], 0, s[74:75]
	v_lshl_add_u64 v[122:123], v[154:155], 0, s[74:75]
	v_lshl_add_u64 v[126:127], v[156:157], 0, s[74:75]
	global_load_dwordx4 v[98:101], v[98:99], off
	s_add_i32 s0, s0, 2
	global_load_dwordx4 v[102:105], v[102:103], off
	global_load_dwordx4 v[106:109], v[106:107], off
	global_load_dwordx4 v[110:113], v[110:111], off
	global_load_dwordx4 v[114:117], v[114:115], off
	global_load_dwordx4 v[118:121], v[118:119], off
	global_load_dwordx4 v[122:125], v[122:123], off
	global_load_dwordx4 v[126:129], v[126:127], off
	s_waitcnt lgkmcnt(0)
	s_barrier
	v_mfma_f32_16x16x32_bf16 v[6:9], v[176:179], v[172:175], v[6:9]
	v_mfma_f32_16x16x32_bf16 v[2:5], v[180:183], v[172:175], v[2:5]
	v_mfma_f32_16x16x32_bf16 v[14:17], v[184:187], v[172:175], v[14:17]
	s_branch .Lrot178_body
.Lrot178_last:
	s_waitcnt lgkmcnt(0)
	s_barrier
	v_mfma_f32_16x16x32_bf16 v[6:9], v[176:179], v[172:175], v[6:9]
	v_mfma_f32_16x16x32_bf16 v[2:5], v[180:183], v[172:175], v[2:5]
	v_mfma_f32_16x16x32_bf16 v[14:17], v[184:187], v[172:175], v[14:17]
	v_lshl_add_u32 v102, s14, 7, v165
	s_waitcnt vmcnt(7)
	v_or_b32_e32 v34, v102, v159
	v_lshlrev_b32_e32 v36, 3, v34
	v_readlane_b32 s56, v253, 61
	v_ashrrev_i32_e32 v37, 31, v36
	v_readlane_b32 s70, v254, 11
	v_readlane_b32 s71, v254, 12
	s_mov_b32 s0, 0x358637bd
	v_mov_b64_e32 v[98:99], s[0:1]
	v_lshl_add_u64 v[100:101], v[36:37], 2, s[70:71]
	global_load_dwordx4 v[36:39], v[100:101], off offset:16
	global_load_dwordx4 v[40:43], v[100:101], off
	s_mov_b32 s2, 0x3a800000
	s_mov_b32 s0, 0x800000
	s_cmp_gt_i32 s12, 8
	v_readlane_b32 s57, v253, 62
	v_readlane_b32 s58, v253, 63
	v_readlane_b32 s59, v254, 0
	v_readlane_b32 s60, v254, 1
	v_readlane_b32 s61, v254, 2
	v_readlane_b32 s62, v254, 3
	v_readlane_b32 s63, v254, 4
	v_readlane_b32 s64, v254, 5
	v_readlane_b32 s65, v254, 6
	v_readlane_b32 s66, v254, 7
	v_readlane_b32 s67, v254, 8
	v_readlane_b32 s68, v254, 9
	v_readlane_b32 s69, v254, 10
	s_waitcnt vmcnt(0)
	v_mov_b32_e32 v44, v41
	v_mov_b32_e32 v45, v42
	v_mov_b32_e32 v41, v43
	v_pk_add_f32 v[44:45], v[44:45], v[40:41]
	v_mov_b32_e32 v40, v38
	v_mov_b32_e32 v41, v36
	v_mov_b32_e32 v36, v39
	v_pk_add_f32 v[46:47], v[40:41], v[36:37]
	global_load_dwordx4 v[36:39], v[100:101], off offset:528
	global_load_dwordx4 v[40:43], v[100:101], off offset:512
	s_waitcnt vmcnt(0)
; __device__ void phase_inproj(const Params& p, int l, unsigned char* smem) {
;     ...
;     const int rowb = mt * 128 + wm * 64 + fr;
;     const int colb = ct * 128 + wn * 64 + fq * 4;
; #pragma unroll
;     for (int mi = 0; mi < 4; ++mi) {
;       const f32x4 s0 = *(const f32x4*)(p.ssqn + (rowb + mi * 16) * 8), s1 = *(const f32x4*)(p.ssqn + (rowb + mi * 16) * 8 + 4);
;       const float rstd = rsqrtf(((s0[0] + s0[1]) + (s0[2] + s0[3]) + (s1[0] + s1[1]) + (s1[2] + s1[3])) * (1.f / 1024.f) + 1e-6f);
; #pragma unroll
;       for (int ni = 0; ni < 4; ++ni) acc[mi][ni] *= rstd;
;     }
;     if (ct < 9) {
; #pragma unroll
;       for (int mi = 0; mi < 4; ++mi)
; #pragma unroll
;         for (int ni = 0; ni < 4; ++ni) store4bf(p.qkvA + (size_t)(rowb + mi * 16) * 1152 + colb + ni * 16, acc[mi][ni]);
;     } else if (ct < 17) {
; #pragma unroll
;       for (int mi = 0; mi < 4; ++mi)
; #pragma unroll
;         for (int ni = 0; ni < 4; ++ni) store4bf(p.qkB + (size_t)(rowb + mi * 16) * 1024 + (colb - 1152) + ni * 16, acc[mi][ni]);
;     } else if (ct < 21) {
;       const int h = ct - 17;
; #pragma unroll
;       for (int mi = 0; mi < 4; ++mi) {
;         const int row = rowb + mi * 16, b = row >> 13, pos = row & 8191;
; #pragma unroll
;         for (int ni = 0; ni < 4; ++ni) {
;           const int dv = wn * 64 + ni * 16 + fq * 4;
;           bf16_t* d = p.vtB + ((size_t)((b * 4 + h) * 128 + dv)) * SEQ + pos;
;           const unsigned u0 = pack2(acc[mi][ni][0], acc[mi][ni][1]), u1 = pack2(acc[mi][ni][2], acc[mi][ni][3]);
;           d[0] = (bf16_t)u0; d[SEQ] = (bf16_t)(u0 >> 16); d[2 * SEQ] = (bf16_t)u1; d[3 * SEQ] = (bf16_t)(u1 >> 16);
;         }
;       }
;     } else if (ct < 24) {
; #pragma unroll
;       for (int mi = 0; mi < 4; ++mi) {
;         const int row = rowb + mi * 16;
;         float s = 0.f;
; #pragma unroll
;         for (int ni = 0; ni < 4; ++ni) {
;           const f32x4 v = acc[mi][ni];
;           s += v[0] * v[0] + v[1] * v[1] + v[2] * v[2] + v[3] * v[3];
;           if (ct < 23) store4bf(p.cq_lat + (size_t)row * 256 + (colb - 2688) + ni * 16, v);
;           else store4bf(p.ckv_lat + (size_t)row * 128 + (colb - 2944) + ni * 16, v);
;         }
;         s = xsum_rows(s);
;         if (fq == 0) { if (ct < 23) p.ssq_cq[row * 4 + (ct - 21) * 2 + wn] = s; else p.ssq_ckv[row * 2 + wn] = s; }
;       }
;     } else if (ct < 48) {
; #pragma unroll
	v_mov_b32_e32 v48, v41
	v_mov_b32_e32 v49, v42
	v_mov_b32_e32 v41, v43
	v_pk_add_f32 v[40:41], v[48:49], v[40:41]
	v_mov_b32_e32 v42, v38
	v_mov_b32_e32 v43, v36
	v_mov_b32_e32 v36, v39
	v_pk_add_f32 v[36:37], v[42:43], v[36:37]
	v_mov_b32_e32 v38, v40
	v_mov_b32_e32 v39, v44
	v_mov_b32_e32 v44, v41
	v_pk_add_f32 v[38:39], v[38:39], v[44:45]
	v_mov_b32_e32 v40, v37
	v_mov_b32_e32 v41, v47
	v_pk_add_f32 v[38:39], v[38:39], v[40:41]
	v_mov_b32_e32 v37, v46
	v_pk_add_f32 v[36:37], v[36:37], v[38:39]
	s_nop 0
	v_pk_fma_f32 v[36:37], v[36:37], s[2:3], v[98:99] op_sel_hi:[1,0,0]
	s_nop 0
	v_mul_f32_e32 v0, 0x4b800000, v37
	v_cmp_gt_f32_e64 s[8:9], s0, v37
	v_cmp_gt_f32_e32 vcc, s0, v36
	s_nop 0
	v_cndmask_b32_e64 v0, v37, v0, s[8:9]
	v_rsq_f32_e32 v0, v0
	s_nop 0
	v_mul_f32_e32 v35, 0x45800000, v0
	v_cndmask_b32_e64 v0, v0, v35, s[8:9]
	v_pk_mul_f32 v[64:65], v[92:93], v[0:1] op_sel_hi:[1,0]
	v_pk_mul_f32 v[90:91], v[90:91], v[0:1] op_sel_hi:[1,0]
	v_pk_mul_f32 v[60:61], v[88:89], v[0:1] op_sel_hi:[1,0]
	v_pk_mul_f32 v[62:63], v[86:87], v[0:1] op_sel_hi:[1,0]
	v_pk_mul_f32 v[56:57], v[80:81], v[0:1] op_sel_hi:[1,0]
	v_pk_mul_f32 v[58:59], v[78:79], v[0:1] op_sel_hi:[1,0]
	v_pk_mul_f32 v[52:53], v[72:73], v[0:1] op_sel_hi:[1,0]
	v_pk_mul_f32 v[54:55], v[70:71], v[0:1] op_sel_hi:[1,0]
	v_mul_f32_e32 v0, 0x4b800000, v36
	v_cndmask_b32_e32 v0, v36, v0, vcc
	v_rsq_f32_e32 v0, v0
	s_nop 0
	v_mul_f32_e32 v35, 0x45800000, v0
	v_cndmask_b32_e32 v0, v0, v35, vcc
	v_pk_mul_f32 v[36:37], v[68:69], v[0:1] op_sel_hi:[1,0]
	v_pk_mul_f32 v[38:39], v[66:67], v[0:1] op_sel_hi:[1,0]
	global_load_dwordx4 v[66:69], v[100:101], off offset:1040
	global_load_dwordx4 v[70:73], v[100:101], off offset:1024
	v_pk_mul_f32 v[42:43], v[74:75], v[0:1] op_sel_hi:[1,0]
	v_pk_mul_f32 v[40:41], v[76:77], v[0:1] op_sel_hi:[1,0]
	v_pk_mul_f32 v[48:49], v[96:97], v[0:1] op_sel_hi:[1,0]
	v_pk_mul_f32 v[50:51], v[94:95], v[0:1] op_sel_hi:[1,0]
	v_pk_mul_f32 v[44:45], v[84:85], v[0:1] op_sel_hi:[1,0]
	v_pk_mul_f32 v[46:47], v[82:83], v[0:1] op_sel_hi:[1,0]
	s_waitcnt vmcnt(0)
	v_mov_b32_e32 v74, v71
	v_mov_b32_e32 v75, v72
	v_mov_b32_e32 v71, v73
	v_pk_add_f32 v[74:75], v[74:75], v[70:71]
	v_mov_b32_e32 v70, v68
	v_mov_b32_e32 v71, v66
	v_mov_b32_e32 v66, v69
	v_pk_add_f32 v[76:77], v[70:71], v[66:67]
	global_load_dwordx4 v[66:69], v[100:101], off offset:1552
	global_load_dwordx4 v[70:73], v[100:101], off offset:1536
	s_waitcnt vmcnt(0)
	v_mov_b32_e32 v78, v71
	v_mov_b32_e32 v79, v72
	v_mov_b32_e32 v71, v73
	v_pk_add_f32 v[70:71], v[78:79], v[70:71]
	v_mov_b32_e32 v72, v68
	v_mov_b32_e32 v73, v66
	v_mov_b32_e32 v66, v69
	v_pk_add_f32 v[66:67], v[72:73], v[66:67]
	v_mov_b32_e32 v68, v70
	v_mov_b32_e32 v69, v74
	v_mov_b32_e32 v74, v71
	v_pk_add_f32 v[68:69], v[68:69], v[74:75]
	v_mov_b32_e32 v70, v67
	v_mov_b32_e32 v71, v77
	v_pk_add_f32 v[68:69], v[68:69], v[70:71]
	v_mov_b32_e32 v67, v76
	v_pk_add_f32 v[66:67], v[66:67], v[68:69]
	s_nop 0
	v_pk_fma_f32 v[66:67], v[66:67], s[2:3], v[98:99] op_sel_hi:[1,0,0]
	s_nop 0
	v_mul_f32_e32 v0, 0x4b800000, v67
	v_cmp_gt_f32_e64 s[8:9], s0, v67
	v_cmp_gt_f32_e32 vcc, s0, v66
	s_mov_b64 s[0:1], -1
	v_cndmask_b32_e64 v0, v67, v0, s[8:9]
	v_rsq_f32_e32 v0, v0
	s_nop 0
	v_mul_f32_e32 v35, 0x45800000, v0
	v_cndmask_b32_e64 v0, v0, v35, s[8:9]
	v_pk_mul_f32 v[32:33], v[32:33], v[0:1] op_sel_hi:[1,0]
	v_pk_mul_f32 v[30:31], v[30:31], v[0:1] op_sel_hi:[1,0]
	v_pk_mul_f32 v[28:29], v[28:29], v[0:1] op_sel_hi:[1,0]
	v_pk_mul_f32 v[26:27], v[26:27], v[0:1] op_sel_hi:[1,0]
	v_pk_mul_f32 v[24:25], v[24:25], v[0:1] op_sel_hi:[1,0]
	v_pk_mul_f32 v[22:23], v[22:23], v[0:1] op_sel_hi:[1,0]
	v_pk_mul_f32 v[20:21], v[20:21], v[0:1] op_sel_hi:[1,0]
	v_pk_mul_f32 v[18:19], v[18:19], v[0:1] op_sel_hi:[1,0]
	v_mul_f32_e32 v0, 0x4b800000, v66
	v_cndmask_b32_e32 v0, v66, v0, vcc
	v_rsq_f32_e32 v0, v0
	s_nop 0
	v_mul_f32_e32 v35, 0x45800000, v0
	v_cndmask_b32_e32 v0, v0, v35, vcc
	v_pk_mul_f32 v[12:13], v[12:13], v[0:1] op_sel_hi:[1,0]
	v_pk_mul_f32 v[68:69], v[10:11], v[0:1] op_sel_hi:[1,0]
	v_pk_mul_f32 v[8:9], v[8:9], v[0:1] op_sel_hi:[1,0]
	v_pk_mul_f32 v[66:67], v[6:7], v[0:1] op_sel_hi:[1,0]
	v_pk_mul_f32 v[6:7], v[4:5], v[0:1] op_sel_hi:[1,0]
	v_pk_mul_f32 v[10:11], v[2:3], v[0:1] op_sel_hi:[1,0]
	v_pk_mul_f32 v[2:3], v[16:17], v[0:1] op_sel_hi:[1,0]
	v_pk_mul_f32 v[4:5], v[14:15], v[0:1] op_sel_hi:[1,0]
	v_lshl_or_b32 v0, s12, 7, v167
	s_cbranch_scc0 .LBB0_249
	s_cmp_gt_u32 s12, 16
	s_cbranch_scc0 .LBB0_246
	s_cmp_gt_u32 s12, 20
	s_cbranch_scc0 .LBB0_243
	s_cmp_gt_u32 s12, 23
	s_cbranch_scc0 .LBB0_190
	s_cmp_gt_u32 s12, 47
	s_cbranch_scc0 .LBB0_187
	s_and_saveexec_b64 s[0:1], s[4:5]
	s_cbranch_execz .LBB0_186
; __device__ __forceinline__ void store4bf(bf16_t* p, f32x4 v) { u32x2 o; o.x = pack2(v[0], v[1]); o.y = pack2(v[2], v[3]); *(u32x2*)p = o; }
; __device__ void phase_inproj(const Params& p, int l, unsigned char* smem) {
;     ...
;       if (wn == 0) {
; #pragma unroll
;         for (int mi = 0; mi < 4; ++mi) {
;           const int row = rowb + mi * 16, pos = row & 8191;
;           const f32x4 c = *(const f32x4*)(p.ropec + pos * 16 + fq * 4), s = *(const f32x4*)(p.ropes + pos * 16 + fq * 4);
;           const f32x4 x1 = acc[mi][0], x2 = acc[mi][1];
;           const f32x4 o1 = x1 * c - x2 * s, o2 = x1 * s + x2 * c;
; #pragma unroll
;           for (int h = 0; h < 6; ++h) {
;             store4bf(p.kC + (size_t)row * 576 + h * 96 + 64 + fq * 4, o1);
;             store4bf(p.kC + (size_t)row * 576 + h * 96 + 80 + fq * 4, o2);
;           }
;         }
;       }
	v_lshlrev_b32_e32 v14, 6, v34
	v_and_b32_e32 v70, 0x7f3c0, v14
	v_mov_b32_e32 v71, v1
	v_lshl_add_u64 v[14:15], v[136:137], 0, v[70:71]
	v_lshl_add_u64 v[70:71], v[138:139], 0, v[70:71]
	global_load_dwordx4 v[70:73], v[70:71], off
	s_movk_i32 s8, 0x480
	global_load_dwordx4 v[14:17], v[14:15], off
	v_or_b32_e32 v35, 16, v34
	s_waitcnt vmcnt(1)
	v_pk_mul_f32 v[76:77], v[62:63], v[70:71]
	v_pk_mul_f32 v[70:71], v[90:91], v[70:71]
	v_pk_mul_f32 v[74:75], v[60:61], v[72:73]
	s_waitcnt vmcnt(0)
	v_pk_fma_f32 v[76:77], v[90:91], v[14:15], v[76:77] neg_lo:[0,0,1] neg_hi:[0,0,1]
	v_pk_mul_f32 v[72:73], v[64:65], v[72:73]
	v_pk_fma_f32 v[14:15], v[62:63], v[14:15], v[70:71]
	v_pk_fma_f32 v[74:75], v[64:65], v[16:17], v[74:75] neg_lo:[0,0,1] neg_hi:[0,0,1]
	v_pk_fma_f32 v[16:17], v[60:61], v[16:17], v[72:73]
	v_mad_i64_i32 v[70:71], s[2:3], v34, s8, v[140:141]
	v_cvt_pk_bf16_f32 v14, v14, v15
	v_cvt_pk_bf16_f32 v15, v16, v17
	v_cvt_pk_bf16_f32 v72, v76, v77
	v_cvt_pk_bf16_f32 v73, v74, v75
	global_store_dwordx2 v[70:71], v[72:73], off offset:128
	global_store_dwordx2 v[70:71], v[14:15], off offset:160
	global_store_dwordx2 v[70:71], v[72:73], off offset:320
	global_store_dwordx2 v[70:71], v[14:15], off offset:352
	global_store_dwordx2 v[70:71], v[72:73], off offset:512
	global_store_dwordx2 v[70:71], v[14:15], off offset:544
	global_store_dwordx2 v[70:71], v[72:73], off offset:704
	global_store_dwordx2 v[70:71], v[14:15], off offset:736
	global_store_dwordx2 v[70:71], v[72:73], off offset:896
	global_store_dwordx2 v[70:71], v[14:15], off offset:928
	global_store_dwordx2 v[70:71], v[72:73], off offset:1088
	global_store_dwordx2 v[70:71], v[14:15], off offset:1120
	v_lshlrev_b32_e32 v14, 6, v35
	v_and_b32_e32 v70, 0x7f7c0, v14
	v_mov_b32_e32 v71, v1
	v_lshl_add_u64 v[14:15], v[136:137], 0, v[70:71]
	v_lshl_add_u64 v[70:71], v[138:139], 0, v[70:71]
	global_load_dwordx4 v[70:73], v[70:71], off
	s_waitcnt vmcnt(0)
	v_pk_mul_f32 v[76:77], v[46:47], v[70:71]
	global_load_dwordx4 v[14:17], v[14:15], off
	v_pk_mul_f32 v[70:71], v[50:51], v[70:71]
	v_pk_mul_f32 v[74:75], v[44:45], v[72:73]
	v_pk_mul_f32 v[72:73], v[48:49], v[72:73]
	s_waitcnt vmcnt(0)
	v_pk_fma_f32 v[76:77], v[50:51], v[14:15], v[76:77] neg_lo:[0,0,1] neg_hi:[0,0,1]
	v_pk_fma_f32 v[14:15], v[46:47], v[14:15], v[70:71]
	v_pk_fma_f32 v[74:75], v[48:49], v[16:17], v[74:75] neg_lo:[0,0,1] neg_hi:[0,0,1]
	v_pk_fma_f32 v[16:17], v[44:45], v[16:17], v[72:73]
	v_mad_i64_i32 v[70:71], s[2:3], v35, s8, v[140:141]
	v_cvt_pk_bf16_f32 v14, v14, v15
	v_cvt_pk_bf16_f32 v15, v16, v17
	v_or_b32_e32 v35, 32, v34
	v_cvt_pk_bf16_f32 v72, v76, v77
	v_cvt_pk_bf16_f32 v73, v74, v75
	global_store_dwordx2 v[70:71], v[72:73], off offset:128
	global_store_dwordx2 v[70:71], v[14:15], off offset:160
	global_store_dwordx2 v[70:71], v[72:73], off offset:320
	global_store_dwordx2 v[70:71], v[14:15], off offset:352
	global_store_dwordx2 v[70:71], v[72:73], off offset:512
	global_store_dwordx2 v[70:71], v[14:15], off offset:544
	global_store_dwordx2 v[70:71], v[72:73], off offset:704
	global_store_dwordx2 v[70:71], v[14:15], off offset:736
	global_store_dwordx2 v[70:71], v[72:73], off offset:896
	global_store_dwordx2 v[70:71], v[14:15], off offset:928
	global_store_dwordx2 v[70:71], v[72:73], off offset:1088
	global_store_dwordx2 v[70:71], v[14:15], off offset:1120
	v_lshlrev_b32_e32 v14, 6, v35
	v_and_b32_e32 v70, 0x7fbc0, v14
	v_mov_b32_e32 v71, v1
	v_lshl_add_u64 v[14:15], v[136:137], 0, v[70:71]
	v_lshl_add_u64 v[70:71], v[138:139], 0, v[70:71]
	global_load_dwordx4 v[70:73], v[70:71], off
	s_waitcnt vmcnt(0)
	v_pk_mul_f32 v[76:77], v[26:27], v[70:71]
	global_load_dwordx4 v[14:17], v[14:15], off
	v_pk_mul_f32 v[70:71], v[30:31], v[70:71]
	v_pk_mul_f32 v[74:75], v[28:29], v[72:73]
	v_pk_mul_f32 v[72:73], v[32:33], v[72:73]
	s_waitcnt vmcnt(0)
	v_pk_fma_f32 v[76:77], v[30:31], v[14:15], v[76:77] neg_lo:[0,0,1] neg_hi:[0,0,1]
	v_pk_fma_f32 v[14:15], v[26:27], v[14:15], v[70:71]
	v_pk_fma_f32 v[74:75], v[32:33], v[16:17], v[74:75] neg_lo:[0,0,1] neg_hi:[0,0,1]
	v_pk_fma_f32 v[16:17], v[28:29], v[16:17], v[72:73]
	v_mad_i64_i32 v[70:71], s[2:3], v35, s8, v[140:141]
	v_cvt_pk_bf16_f32 v14, v14, v15
	v_cvt_pk_bf16_f32 v15, v16, v17
	v_or_b32_e32 v35, 48, v34
	v_cvt_pk_bf16_f32 v72, v76, v77
	v_cvt_pk_bf16_f32 v73, v74, v75
	global_store_dwordx2 v[70:71], v[72:73], off offset:128
	global_store_dwordx2 v[70:71], v[14:15], off offset:160
	global_store_dwordx2 v[70:71], v[72:73], off offset:320
	global_store_dwordx2 v[70:71], v[14:15], off offset:352
	global_store_dwordx2 v[70:71], v[72:73], off offset:512
	global_store_dwordx2 v[70:71], v[14:15], off offset:544
	global_store_dwordx2 v[70:71], v[72:73], off offset:704
	global_store_dwordx2 v[70:71], v[14:15], off offset:736
	global_store_dwordx2 v[70:71], v[72:73], off offset:896
	global_store_dwordx2 v[70:71], v[14:15], off offset:928
	global_store_dwordx2 v[70:71], v[72:73], off offset:1088
	global_store_dwordx2 v[70:71], v[14:15], off offset:1120
	v_lshlrev_b32_e32 v14, 6, v35
	v_and_b32_e32 v70, 0x7ffc0, v14
	v_mov_b32_e32 v71, v1
	v_lshl_add_u64 v[14:15], v[136:137], 0, v[70:71]
	v_lshl_add_u64 v[70:71], v[138:139], 0, v[70:71]
	global_load_dwordx4 v[70:73], v[70:71], off
	s_waitcnt vmcnt(0)
	v_pk_mul_f32 v[76:77], v[66:67], v[70:71]
	global_load_dwordx4 v[14:17], v[14:15], off
	v_pk_mul_f32 v[70:71], v[68:69], v[70:71]
	v_pk_mul_f32 v[74:75], v[8:9], v[72:73]
	v_pk_mul_f32 v[72:73], v[12:13], v[72:73]
	s_waitcnt vmcnt(0)
	v_pk_fma_f32 v[76:77], v[68:69], v[14:15], v[76:77] neg_lo:[0,0,1] neg_hi:[0,0,1]
	v_pk_fma_f32 v[14:15], v[66:67], v[14:15], v[70:71]
	v_pk_fma_f32 v[74:75], v[12:13], v[16:17], v[74:75] neg_lo:[0,0,1] neg_hi:[0,0,1]
	v_pk_fma_f32 v[16:17], v[8:9], v[16:17], v[72:73]
	v_mad_i64_i32 v[70:71], s[2:3], v35, s8, v[140:141]
	v_cvt_pk_bf16_f32 v14, v14, v15
	v_cvt_pk_bf16_f32 v15, v16, v17
	v_cvt_pk_bf16_f32 v72, v76, v77
	v_cvt_pk_bf16_f32 v73, v74, v75
	global_store_dwordx2 v[70:71], v[72:73], off offset:128
	global_store_dwordx2 v[70:71], v[14:15], off offset:160
	global_store_dwordx2 v[70:71], v[72:73], off offset:320
	global_store_dwordx2 v[70:71], v[14:15], off offset:352
	global_store_dwordx2 v[70:71], v[72:73], off offset:512
	global_store_dwordx2 v[70:71], v[14:15], off offset:544
	global_store_dwordx2 v[70:71], v[72:73], off offset:704
	global_store_dwordx2 v[70:71], v[14:15], off offset:736
	global_store_dwordx2 v[70:71], v[72:73], off offset:896
	global_store_dwordx2 v[70:71], v[14:15], off offset:928
	global_store_dwordx2 v[70:71], v[72:73], off offset:1088
	global_store_dwordx2 v[70:71], v[14:15], off offset:1120

; __device__ __forceinline__ void peer_convert_chunk(const Params& p, int l, size_t i) {
;   const size_t base = (size_t)l * 16384 * 1024 + i * 16;
;   u32x4 ou, ov;
; #pragma unroll
;   for (int c = 0; c < 4; ++c) {
;     const f32x4 a = *(const f32x4*)(p.peer_u + base + c * 4) * 256.f;
;     int r = 0; r = __builtin_amdgcn_cvt_pk_fp8_f32(a[0], a[1], r, false); r = __builtin_amdgcn_cvt_pk_fp8_f32(a[2], a[3], r, true); ou[c] = (unsigned)r;
;     const f32x4 d = *(const f32x4*)(p.peer_v + base + c * 4) * 64.f;
;     int q = 0; q = __builtin_amdgcn_cvt_pk_fp8_f32(d[0], d[1], q, false); q = __builtin_amdgcn_cvt_pk_fp8_f32(d[2], d[3], q, true); ov[c] = (unsigned)q;
;   }
;   *(u32x4*)(p.pu8 + base) = ou;
;   *(u32x4*)(p.pv8 + base) = ov;
; }
; __device__ void phase_inproj(const Params& p, int l, unsigned char* smem) {
;     ...
;     {
;       const size_t ci = ((size_t)it * gridDim.x + blockIdx.x) * NTHREADS + tid;
;       if (ci < N16L) peer_convert_chunk(p, l, ci);
;     }
.LBB0_251:
	s_mul_i32 s0, s16, s52
	v_readlane_b32 s2, v252, 0
	s_mul_hi_u32 s1, s16, s52
	s_add_u32 s0, s0, s2
	s_addc_u32 s1, s1, 0
	s_lshl_b64 s[0:1], s[0:1], 8
	v_lshl_add_u64 v[2:3], s[0:1], 0, v[130:131]
	s_mov_b64 s[0:1], 0x100000
	v_cmp_gt_u64_e32 vcc, s[0:1], v[2:3]
	s_and_saveexec_b64 s[0:1], vcc
	s_cbranch_execz .LBB0_172
	v_readlane_b32 s2, v254, 38
	v_lshlrev_b64 v[2:3], 4, v[2:3]
	v_readlane_b32 s3, v254, 39
	v_or_b32_e32 v10, s2, v2
	v_readlane_b32 s8, v253, 55
	v_or_b32_e32 v11, s3, v3
	v_lshlrev_b64 v[2:3], 2, v[10:11]
	v_readlane_b32 s10, v253, 57
	v_readlane_b32 s11, v253, 58
	v_readlane_b32 s2, v253, 49
	v_readlane_b32 s3, v253, 50
	v_lshl_add_u64 v[4:5], s[10:11], 0, v[2:3]
	v_readlane_b32 s9, v253, 56
	v_lshl_add_u64 v[6:7], s[2:3], 0, v[2:3]
	v_mov_b32_e32 v12, v212
	v_mov_b32_e32 v13, v213
	v_mov_b32_e32 v14, v214
	v_mov_b32_e32 v15, v215
	v_mov_b32_e32 v16, v216
	v_mov_b32_e32 v17, v217
	v_mov_b32_e32 v18, v218
	v_mov_b32_e32 v19, v219
	v_mov_b32_e32 v20, v220
	v_mov_b32_e32 v21, v221
	v_mov_b32_e32 v22, v222
	v_mov_b32_e32 v23, v223
	v_mov_b32_e32 v2, v224
	v_mov_b32_e32 v3, v225
	v_mov_b32_e32 v4, v226
	v_mov_b32_e32 v5, v227
	s_mov_b32 s2, 0x43800000
	s_mov_b32 s8, 0x42800000
	v_readlane_b32 s56, v253, 31
	v_readlane_b32 s70, v253, 45
	v_readlane_b32 s71, v253, 46
	v_readlane_b32 s20, v253, 21
	v_readlane_b32 s21, v253, 22
	v_readlane_b32 s57, v253, 32
	v_readlane_b32 s58, v253, 33
	v_readlane_b32 s59, v253, 34
	v_readlane_b32 s60, v253, 35
	v_readlane_b32 s61, v253, 36
	v_readlane_b32 s62, v253, 37
	v_readlane_b32 s63, v253, 38
	v_readlane_b32 s64, v253, 39
	v_readlane_b32 s65, v253, 40
	v_readlane_b32 s66, v253, 41
	v_readlane_b32 s67, v253, 42
	v_readlane_b32 s68, v253, 43
	v_readlane_b32 s69, v253, 44
	v_readlane_b32 s22, v253, 23
	v_readlane_b32 s23, v253, 24
	v_readlane_b32 s24, v253, 25
	v_readlane_b32 s25, v253, 26
	v_readlane_b32 s26, v253, 27
	v_readlane_b32 s27, v253, 28
	v_pk_mul_f32 v[12:13], v[12:13], s[2:3] op_sel_hi:[1,0]
	v_pk_mul_f32 v[16:17], v[16:17], s[2:3] op_sel_hi:[1,0]
	v_pk_mul_f32 v[14:15], v[14:15], s[2:3] op_sel_hi:[1,0]
	v_pk_mul_f32 v[8:9], v[2:3], s[2:3] op_sel_hi:[1,0]
	v_mov_b32_e32 v2, v1
	v_cvt_pk_fp8_f32 v2, v8, v9
	v_pk_mul_f32 v[4:5], v[4:5], s[2:3] op_sel_hi:[1,0]
	v_mov_b32_e32 v3, v1
	v_cvt_pk_fp8_f32 v2, v4, v5 op_sel:[0,0,1]
	v_mov_b32_e32 v24, v228
	v_mov_b32_e32 v25, v229
	v_mov_b32_e32 v26, v230
	v_mov_b32_e32 v27, v231
	v_mov_b32_e32 v28, v232
	v_mov_b32_e32 v29, v233
	v_mov_b32_e32 v30, v234
	v_mov_b32_e32 v31, v235
	v_mov_b32_e32 v32, v236
	v_mov_b32_e32 v33, v237
	v_mov_b32_e32 v34, v238
	v_mov_b32_e32 v35, v239
	v_mov_b32_e32 v4, v240
	v_mov_b32_e32 v5, v241
	v_mov_b32_e32 v6, v242
	v_mov_b32_e32 v7, v243
	v_pk_mul_f32 v[8:9], v[6:7], s[8:9] op_sel_hi:[1,0]
	v_pk_mul_f32 v[4:5], v[4:5], s[8:9] op_sel_hi:[1,0]
	v_mov_b32_e32 v6, v1
	v_cvt_pk_fp8_f32 v6, v4, v5
	v_mov_b32_e32 v7, v1
	v_pk_mul_f32 v[4:5], v[22:23], s[2:3] op_sel_hi:[1,0]
	v_cvt_pk_fp8_f32 v6, v8, v9 op_sel:[0,0,1]
	v_pk_mul_f32 v[8:9], v[20:21], s[2:3] op_sel_hi:[1,0]
	s_nop 0
	v_cvt_pk_fp8_f32 v3, v8, v9
	v_pk_mul_f32 v[8:9], v[32:33], s[8:9] op_sel_hi:[1,0]
	v_cvt_pk_fp8_f32 v3, v4, v5 op_sel:[0,0,1]
	v_cvt_pk_fp8_f32 v7, v8, v9
	v_pk_mul_f32 v[4:5], v[34:35], s[8:9] op_sel_hi:[1,0]
	v_pk_mul_f32 v[8:9], v[18:19], s[2:3] op_sel_hi:[1,0]
	v_pk_mul_f32 v[18:19], v[28:29], s[8:9] op_sel_hi:[1,0]
	v_cvt_pk_fp8_f32 v7, v4, v5 op_sel:[0,0,1]
	v_mov_b32_e32 v4, v1
	v_mov_b32_e32 v5, v1
	v_cvt_pk_fp8_f32 v4, v16, v17
	v_cvt_pk_fp8_f32 v5, v12, v13
	v_pk_mul_f32 v[16:17], v[30:31], s[8:9] op_sel_hi:[1,0]
	v_pk_mul_f32 v[12:13], v[26:27], s[8:9] op_sel_hi:[1,0]
	v_cvt_pk_fp8_f32 v4, v8, v9 op_sel:[0,0,1]
	v_mov_b32_e32 v8, v1
	v_cvt_pk_fp8_f32 v5, v14, v15 op_sel:[0,0,1]
	v_pk_mul_f32 v[14:15], v[24:25], s[8:9] op_sel_hi:[1,0]
	v_mov_b32_e32 v9, v1
	v_cvt_pk_fp8_f32 v8, v18, v19
	v_cvt_pk_fp8_f32 v9, v14, v15
	v_cvt_pk_fp8_f32 v8, v16, v17 op_sel:[0,0,1]
	v_cvt_pk_fp8_f32 v9, v12, v13 op_sel:[0,0,1]
	v_lshl_add_u64 v[12:13], s[70:71], 0, v[10:11]
	global_store_dwordx4 v[12:13], v[2:5], off
	s_nop 1
	v_lshl_add_u64 v[2:3], s[20:21], 0, v[10:11]
	global_store_dwordx4 v[2:3], v[6:9], off
	s_branch .LBB0_172

; #define ATT_SCHED_BARRIER __builtin_amdgcn_sched_barrier(0)
; template <int DQK, int DV, int MODE> ...
;     ...
;   auto gload = [&](int kt) {
; #pragma unroll
;     for (int i = 0; i < NKC; ++i) { const int c = tid + 256 * i, key = c / KCH, part = c % KCH; rk[i] = *(const u32x4*)(Kp + (unsigned)((kt * 64 + key) * krs + part * 8)); }
;     if (MODE == 0) {
; #pragma unroll
;       for (int i = 0; i < NVC; ++i) { const int c = tid + 256 * i, key = c >> 3, part = c & 7; rv[i] = *(const u32x4*)(Vp + (unsigned)((kt * 64 + key) * vrs + part * 8)); }
;     } else {
; #pragma unroll
;       for (int i = 0; i < NVC; ++i) { const int c = tid + 256 * i, dv = c >> 3, kc = c & 7; rv[i] = *(const u32x4*)(Vp + (unsigned)(dv * vrs + kt * 64 + kc * 8)); }
;     }
;     ...
;   for (int kt = kt_begin; kt < kt_end; ++kt) {
;     const bool more = kt + 1 < kt_end;
;     if (more) gload(kt + 1);
;     ATT_SCHED_BARRIER;
;     bf16_t* Qs2 = Qs; asm volatile("" : "+v"(Qs2));
;     if (kt >= wkb && kt < wke) {
;       int path = 1; float cb = 0.f; bool need_mask = true;
;       if (MODE == 2) { need_mask = (kt * 64 + 63) > (qpos0 + w * 32); path = need_mask ? 1 : 0; }
;       if (MODE == 1) {
;         need_mask = (kt * 64 + 63) > (qpos0 + w * 32);
;         const int dmin = (qpos0 + w * 32) - (kt * 64 + 63);
;         if (dmin >= 0) {
;           const float blo = bias_lds[min(dmin, 2047)], bhi = bias_lds[min(dmin + 94, 2047)];
;           if (((__float_as_uint(blo) ^ __float_as_uint(bhi)) & 31u) == 0u) { path = 0; cb = blo; }
;         }
;       }
;       constexpr int QG = (DV == 128) ? ATT_QG_B : 2;
; #pragma unroll
;       for (int q0 = 0; q0 < 2; q0 += QG) {
;         f32x4 S[QG][4];
; #pragma unroll
;         for (int t = 0; t < 4; ++t) {
;           {
;             const bf16x8 kf = *(const bf16x8*)(Ks + (t * 16 + fr) * KST + fq * 8);
; #pragma unroll
;             for (int qq = 0; qq < QG; ++qq) S[qq][t] = __builtin_amdgcn_mfma_f32_16x16x32_bf16(kf, *(const bf16x8*)(Qs2 + ((q0 + qq) * NKS) * 512), (f32x4){0.f, 0.f, 0.f, 0.f}, 0, 0, 0);
;           }
; #pragma unroll
;           for (int ks = 1; ks < NKS; ++ks) {
;             const bf16x8 kf = *(const bf16x8*)(Ks + (t * 16 + fr) * KST + ks * 32 + fq * 8);
; #pragma unroll
;             for (int qq = 0; qq < QG; ++qq) S[qq][t] = mfma16(kf, *(const bf16x8*)(Qs2 + ((q0 + qq) * NKS + ks) * 512), S[qq][t]);
;           }
;         }
.LBB0_533:
	s_cmp_lt_u32 s25, s23
	s_cselect_b64 s[0:1], -1, 0
	s_cmp_ge_u32 s25, s23
	s_cbranch_scc1 .LBB0_535
	v_readlane_b32 s2, v252, 21
	v_readlane_b32 s3, v252, 22
	s_lshl_b32 s12, s26, 1
	s_add_i32 s12, s12, 2
	s_waitcnt vmcnt(0)
	v_lshlrev_b32_e32 v2, 1, v0
	v_lshlrev_b32_e32 v6, 1, v164
	v_lshl_add_u32 v14, v136, 1, s12
	v_lshl_add_u32 v18, v138, 1, s12
	v_lshl_add_u32 v26, v150, 1, s12
	v_lshl_add_u32 v30, v152, 1, s12
	global_load_dwordx4 v[2:5], v2, s[18:19] offset:1024
	global_load_dwordx4 v[6:9], v6, s[18:19] offset:1024
	global_load_dwordx4 v[14:17], v14, s[2:3]
	global_load_dwordx4 v[18:21], v18, s[2:3]
	global_load_dwordx4 v[26:29], v26, s[2:3]
	global_load_dwordx4 v[30:33], v30, s[2:3]
.LBB0_535:
	v_cmp_le_i32_e32 vcc, s25, v227
	s_and_saveexec_b64 s[2:3], vcc
	s_cbranch_execz .LBB0_547
	v_cmp_lt_i32_e32 vcc, -1, v232
	s_mov_b64 s[12:13], 0
	v_mov_b32_e32 v242, 0
	s_and_saveexec_b64 s[4:5], vcc
	s_cbranch_execz .LBB0_538
	v_min_u32_e32 v92, 0x7ff, v232
	v_min_u32_e32 v93, 0x7a1, v232
	v_lshl_add_u32 v92, v92, 2, 0
	v_lshl_add_u32 v93, v93, 2, 0
	ds_read_b32 v92, v92 offset:34816
	ds_read_b32 v93, v93 offset:35192
	s_waitcnt lgkmcnt(0)
	v_bitop3_b32 v93, v93, 31, v92 bitop3:0x48
	v_cmp_eq_u32_e32 vcc, 0, v93
	s_and_b64 s[12:13], vcc, exec
	s_nop 0
	v_cndmask_b32_e32 v242, 0, v92, vcc
.LBB0_538:
	s_or_b64 exec, exec, s[4:5]
	ds_read_b128 v[114:117], v124
	ds_read_b128 v[170:173], v124 offset:1024
	ds_read_b128 v[166:169], v124 offset:2048
	ds_read_b128 v[174:177], v124 offset:3072
	ds_read_b128 v[92:95], v207
	ds_read_b128 v[102:105], v207 offset:64
	s_xor_b64 s[4:5], s[12:13], -1
	v_cmp_gt_i32_e32 vcc, s26, v226
	s_waitcnt lgkmcnt(0)
	v_mfma_f32_16x16x32_bf16 v[96:99], v[92:95], v[114:117], 0
	ds_read_b128 v[178:181], v207 offset:5184
	v_mfma_f32_16x16x32_bf16 v[92:95], v[92:95], v[166:169], 0
	v_mfma_f32_16x16x32_bf16 v[110:113], v[102:105], v[174:177], v[92:95]
	v_mfma_f32_16x16x32_bf16 v[98:101], v[102:105], v[170:173], v[96:99]
	s_nop 5
	ds_read_b128 v[90:93], v207 offset:2560
	ds_read_b128 v[102:105], v207 offset:2624
	s_waitcnt lgkmcnt(1)
	v_mfma_f32_16x16x32_bf16 v[94:97], v[90:93], v[114:117], 0
	v_mfma_f32_16x16x32_bf16 v[90:93], v[90:93], v[166:169], 0
	s_waitcnt lgkmcnt(0)
	v_mfma_f32_16x16x32_bf16 v[106:109], v[102:105], v[174:177], v[90:93]
	v_mfma_f32_16x16x32_bf16 v[118:121], v[102:105], v[170:173], v[94:97]
	s_nop 4
	ds_read_b128 v[90:93], v207 offset:5120
	s_waitcnt lgkmcnt(0)
	v_mfma_f32_16x16x32_bf16 v[94:97], v[90:93], v[114:117], 0
	v_mfma_f32_16x16x32_bf16 v[102:105], v[90:93], v[166:169], 0
	v_mfma_f32_16x16x32_bf16 v[90:93], v[178:181], v[170:173], v[94:97]
	s_nop 5
	ds_read_b128 v[94:97], v207 offset:7680
	s_waitcnt lgkmcnt(0)
	v_mfma_f32_16x16x32_bf16 v[114:117], v[94:97], v[114:117], 0
	v_mfma_f32_16x16x32_bf16 v[94:97], v[94:97], v[166:169], 0
	ds_read_b128 v[166:169], v207 offset:7744
	v_mfma_f32_16x16x32_bf16 v[102:105], v[178:181], v[174:177], v[102:105]
	s_waitcnt lgkmcnt(0)
	v_mfma_f32_16x16x32_bf16 v[114:117], v[166:169], v[170:173], v[114:117]
	v_mfma_f32_16x16x32_bf16 v[94:97], v[166:169], v[174:177], v[94:97]
	v_add_u32_e32 v246, v222, v232
	s_and_saveexec_b64 s[12:13], s[4:5]
	s_xor_b64 s[20:21], exec, s[12:13]
	s_cbranch_execz .LBB0_540
	s_cbranch_vccz .Lb1a_q1
; __device__ __forceinline__ float fmax3(float a, float b, float c) { float r; asm("v_max3_f32 %0, %1, %2, %3" : "=v"(r) : "v"(a), "v"(b), "v"(c)); return r; }
; template <int DQK, int DV, int MODE> ...
;     ...
;             float mx = -1e30f;
; #pragma unroll
;             for (int t = 0; t < 4; ++t)
; #pragma unroll
;               for (int r = 0; r < 4; ++r) {
;                 const int j = kt * 64 + t * 16 + fq * 4 + r;
;                 float sx = S[qq][t][r] * c1;
;                 if (MODE == 1) {
;                   const int dist = qpos0 + qrow - j;
;                   sx += bias_lds[min(max(dist, 0), 2047)];
;                   if (need_mask && dist < 0) sx = -1e30f;
;                 } else if (MODE == 2) {
;                   if ((qpos0 + qrow - j) < 0) sx = -1e30f;
;                 } else {
;                   const int rel = 128 + qrow - j;
;                   sx += bias_lds[min(max(rel, 0), 128)];
;                   if (rel < 0 || rel > 128 || j < jmin) sx = -1e30f;
;                 }
;                 P[t][r] = sx;
;               }
; #pragma unroll
;             for (int t = 0; t < 4; ++t) { mx = fmax3(mx, P[t][0], P[t][1]); mx = fmax3(mx, P[t][2], P[t][3]); }
;             mx = xmax_rows(mx);
;             mn = fmax3(mrow[qi], mx, mx);
; #pragma unroll
;             for (int t = 0; t < 4; ++t) P[t] = P[t] - mn;
	v_add_u32_e32 v245, 63, v246
	v_add_u32_e32 v244, 62, v246
	v_add_u32_e32 v243, 61, v246
	v_add_u32_e32 v241, 60, v246
	v_add_u32_e32 v240, 47, v246
	v_add_u32_e32 v239, 46, v246
	v_add_u32_e32 v238, 45, v246
	v_add_u32_e32 v237, 44, v246
	v_add_u32_e32 v188, 31, v246
	v_add_u32_e32 v186, 30, v246
	v_add_u32_e32 v184, 29, v246
	v_add_u32_e32 v182, 28, v246
	v_med3_i32 v165, v245, 0, v198
	v_med3_i32 v166, v244, 0, v198
	v_med3_i32 v167, v243, 0, v198
	v_med3_i32 v168, v241, 0, v198
	v_med3_i32 v169, v240, 0, v198
	v_med3_i32 v170, v239, 0, v198
	v_med3_i32 v171, v238, 0, v198
	v_med3_i32 v172, v237, 0, v198
	v_lshl_add_u32 v165, v165, 2, 0
	v_lshl_add_u32 v166, v166, 2, 0
	v_lshl_add_u32 v167, v167, 2, 0
	v_lshl_add_u32 v168, v168, 2, 0
	v_lshl_add_u32 v169, v169, 2, 0
	v_lshl_add_u32 v170, v170, 2, 0
	v_lshl_add_u32 v171, v171, 2, 0
	v_lshl_add_u32 v172, v172, 2, 0
	ds_read_b32 v165, v165 offset:34816
	ds_read_b32 v166, v166 offset:34816
	ds_read_b32 v167, v167 offset:34816
	ds_read_b32 v168, v168 offset:34816
	ds_read_b32 v169, v169 offset:34816
	ds_read_b32 v170, v170 offset:34816
	ds_read_b32 v171, v171 offset:34816
	ds_read_b32 v172, v172 offset:34816
	v_cmp_gt_i32_e64 s[12:13], 0, v245
	s_waitcnt lgkmcnt(7)
	v_fmac_f32_e32 v165, 0x3e38aa3b, v98
	s_and_b64 s[12:13], vcc, s[12:13]
	v_cndmask_b32_e64 v98, v165, v194, s[12:13]
	v_cmp_gt_i32_e64 s[12:13], 0, v244
	s_waitcnt lgkmcnt(6)
	v_fmac_f32_e32 v166, 0x3e38aa3b, v99
	s_and_b64 s[12:13], vcc, s[12:13]
	v_cndmask_b32_e64 v99, v166, v194, s[12:13]
	v_cmp_gt_i32_e64 s[12:13], 0, v243
	s_waitcnt lgkmcnt(5)
	v_fmac_f32_e32 v167, 0x3e38aa3b, v100
	s_and_b64 s[12:13], vcc, s[12:13]
	v_cndmask_b32_e64 v100, v167, v194, s[12:13]
	v_cmp_gt_i32_e64 s[12:13], 0, v241
	s_waitcnt lgkmcnt(4)
	v_fmac_f32_e32 v168, 0x3e38aa3b, v101
	s_and_b64 s[12:13], vcc, s[12:13]
	v_cndmask_b32_e64 v101, v168, v194, s[12:13]
	v_cmp_gt_i32_e64 s[12:13], 0, v240
	s_waitcnt lgkmcnt(3)
	v_fmac_f32_e32 v169, 0x3e38aa3b, v118
	s_and_b64 s[12:13], vcc, s[12:13]
	v_cndmask_b32_e64 v118, v169, v194, s[12:13]
	v_cmp_gt_i32_e64 s[12:13], 0, v239
	s_waitcnt lgkmcnt(2)
	v_fmac_f32_e32 v170, 0x3e38aa3b, v119
	s_and_b64 s[12:13], vcc, s[12:13]
	v_cndmask_b32_e64 v119, v170, v194, s[12:13]
	v_cmp_gt_i32_e64 s[12:13], 0, v238
	s_waitcnt lgkmcnt(1)
	v_fmac_f32_e32 v171, 0x3e38aa3b, v120
	s_and_b64 s[12:13], vcc, s[12:13]
	v_cndmask_b32_e64 v120, v171, v194, s[12:13]
	v_cmp_gt_i32_e64 s[12:13], 0, v237
	s_waitcnt lgkmcnt(0)
	v_fmac_f32_e32 v172, 0x3e38aa3b, v121
	s_and_b64 s[12:13], vcc, s[12:13]
	v_add_u32_e32 v169, 15, v246
	v_add_u32_e32 v171, 14, v246
	v_add_u32_e32 v173, 13, v246
	v_add_u32_e32 v175, 12, v246
	v_cndmask_b32_e64 v121, v172, v194, s[12:13]
	v_med3_i32 v165, v188, 0, v198
	v_med3_i32 v166, v186, 0, v198
	v_med3_i32 v167, v184, 0, v198
	v_med3_i32 v168, v182, 0, v198
	v_med3_i32 v170, v169, 0, v198
	v_med3_i32 v172, v171, 0, v198
	v_med3_i32 v174, v173, 0, v198
	v_med3_i32 v176, v175, 0, v198
	v_lshl_add_u32 v165, v165, 2, 0
	v_lshl_add_u32 v166, v166, 2, 0
	v_lshl_add_u32 v167, v167, 2, 0
	v_lshl_add_u32 v168, v168, 2, 0
	v_lshl_add_u32 v170, v170, 2, 0
	v_lshl_add_u32 v172, v172, 2, 0
	v_lshl_add_u32 v174, v174, 2, 0
	v_lshl_add_u32 v176, v176, 2, 0
	ds_read_b32 v165, v165 offset:34816
	ds_read_b32 v166, v166 offset:34816
	ds_read_b32 v167, v167 offset:34816
	ds_read_b32 v168, v168 offset:34816
	ds_read_b32 v170, v170 offset:34816
	ds_read_b32 v172, v172 offset:34816
	ds_read_b32 v174, v174 offset:34816
	ds_read_b32 v176, v176 offset:34816
	v_cmp_gt_i32_e64 s[12:13], 0, v188
	s_waitcnt lgkmcnt(7)
	v_fmac_f32_e32 v165, 0x3e38aa3b, v90
	s_and_b64 s[12:13], vcc, s[12:13]
	v_cndmask_b32_e64 v90, v165, v194, s[12:13]
	v_cmp_gt_i32_e64 s[12:13], 0, v186
	s_waitcnt lgkmcnt(6)
	v_fmac_f32_e32 v166, 0x3e38aa3b, v91
	s_and_b64 s[12:13], vcc, s[12:13]
	v_cndmask_b32_e64 v91, v166, v194, s[12:13]
	v_cmp_gt_i32_e64 s[12:13], 0, v184
	s_waitcnt lgkmcnt(5)
	v_fmac_f32_e32 v167, 0x3e38aa3b, v92
	s_and_b64 s[12:13], vcc, s[12:13]
	v_cndmask_b32_e64 v92, v167, v194, s[12:13]
	v_cmp_gt_i32_e64 s[12:13], 0, v182
	s_waitcnt lgkmcnt(4)
	v_fmac_f32_e32 v168, 0x3e38aa3b, v93
	s_and_b64 s[12:13], vcc, s[12:13]
	v_cndmask_b32_e64 v93, v168, v194, s[12:13]
	v_cmp_gt_i32_e64 s[12:13], 0, v169
	s_waitcnt lgkmcnt(3)
	v_fmac_f32_e32 v170, 0x3e38aa3b, v114
	s_and_b64 s[12:13], vcc, s[12:13]
	v_max3_f32 v165, v194, v98, v99
	v_cndmask_b32_e64 v114, v170, v194, s[12:13]
	v_cmp_gt_i32_e64 s[12:13], 0, v171
	v_max3_f32 v165, v165, v100, v101
	s_waitcnt lgkmcnt(2)
	v_fmac_f32_e32 v172, 0x3e38aa3b, v115
	s_and_b64 s[12:13], vcc, s[12:13]
	v_max3_f32 v165, v165, v118, v119
	v_cndmask_b32_e64 v115, v172, v194, s[12:13]
	v_cmp_gt_i32_e64 s[12:13], 0, v173
	v_max3_f32 v165, v165, v120, v121
	s_waitcnt lgkmcnt(1)
	v_fmac_f32_e32 v174, 0x3e38aa3b, v116
	s_and_b64 s[12:13], vcc, s[12:13]
	v_max3_f32 v165, v165, v90, v91
	v_cndmask_b32_e64 v116, v174, v194, s[12:13]
	v_cmp_gt_i32_e64 s[12:13], 0, v175
	v_max3_f32 v165, v165, v92, v93
	s_waitcnt lgkmcnt(0)
	v_fmac_f32_e32 v176, 0x3e38aa3b, v117
	s_and_b64 s[12:13], vcc, s[12:13]
	v_max3_f32 v165, v165, v114, v115
	v_cndmask_b32_e64 v117, v176, v194, s[12:13]
	v_max3_f32 v165, v165, v116, v117
	s_nop 0
	v_mov_b32_e32 v166, v165
	s_nop 1
	v_permlane16_swap_b32_e32 v165, v166
	v_max3_f32 v165, v165, v166, v166
	s_nop 0
	v_mov_b32_e32 v166, v165
	s_nop 1
	v_permlane32_swap_b32_e32 v165, v166
	v_max3_f32 v165, v165, v166, v166
	s_nop 0
	v_max3_f32 v165, v236, v165, v165
	s_nop 0
	v_sub_f32_e32 v176, v98, v165
	v_sub_f32_e32 v177, v99, v165
	v_sub_f32_e32 v172, v100, v165
	v_sub_f32_e32 v173, v101, v165
	v_sub_f32_e32 v166, v118, v165
	v_sub_f32_e32 v167, v119, v165
	v_sub_f32_e32 v174, v120, v165
	v_sub_f32_e32 v175, v121, v165
	v_sub_f32_e32 v170, v90, v165
	v_sub_f32_e32 v171, v91, v165
	v_sub_f32_e32 v180, v92, v165
	v_sub_f32_e32 v181, v93, v165
	v_sub_f32_e32 v178, v114, v165
	v_sub_f32_e32 v179, v115, v165
	v_sub_f32_e32 v168, v116, v165
	v_sub_f32_e32 v169, v117, v165

; #define ATT_SCHED_BARRIER __builtin_amdgcn_sched_barrier(0)
; template <int DQK, int DV, int MODE> ...
;     ...
;   auto gload = [&](int kt) {
; #pragma unroll
;     for (int i = 0; i < NKC; ++i) { const int c = tid + 256 * i, key = c / KCH, part = c % KCH; rk[i] = *(const u32x4*)(Kp + (unsigned)((kt * 64 + key) * krs + part * 8)); }
;     if (MODE == 0) {
; #pragma unroll
;       for (int i = 0; i < NVC; ++i) { const int c = tid + 256 * i, key = c >> 3, part = c & 7; rv[i] = *(const u32x4*)(Vp + (unsigned)((kt * 64 + key) * vrs + part * 8)); }
;     } else {
; #pragma unroll
;       for (int i = 0; i < NVC; ++i) { const int c = tid + 256 * i, dv = c >> 3, kc = c & 7; rv[i] = *(const u32x4*)(Vp + (unsigned)(dv * vrs + kt * 64 + kc * 8)); }
;     }
;     ...
;   for (int kt = kt_begin; kt < kt_end; ++kt) {
;     const bool more = kt + 1 < kt_end;
;     if (more) gload(kt + 1);
;     ATT_SCHED_BARRIER;
;     bf16_t* Qs2 = Qs; asm volatile("" : "+v"(Qs2));
;     if (kt >= wkb && kt < wke) {
;       int path = 1; float cb = 0.f; bool need_mask = true;
;       if (MODE == 2) { need_mask = (kt * 64 + 63) > (qpos0 + w * 32); path = need_mask ? 1 : 0; }
;       if (MODE == 1) {
;         need_mask = (kt * 64 + 63) > (qpos0 + w * 32);
;         const int dmin = (qpos0 + w * 32) - (kt * 64 + 63);
;         if (dmin >= 0) {
;           const float blo = bias_lds[min(dmin, 2047)], bhi = bias_lds[min(dmin + 94, 2047)];
;           if (((__float_as_uint(blo) ^ __float_as_uint(bhi)) & 31u) == 0u) { path = 0; cb = blo; }
;         }
;       }
;       constexpr int QG = (DV == 128) ? ATT_QG_B : 2;
; #pragma unroll
;       for (int q0 = 0; q0 < 2; q0 += QG) {
;         f32x4 S[QG][4];
; #pragma unroll
;         for (int t = 0; t < 4; ++t) {
;           {
;             const bf16x8 kf = *(const bf16x8*)(Ks + (t * 16 + fr) * KST + fq * 8);
; #pragma unroll
;             for (int qq = 0; qq < QG; ++qq) S[qq][t] = __builtin_amdgcn_mfma_f32_16x16x32_bf16(kf, *(const bf16x8*)(Qs2 + ((q0 + qq) * NKS) * 512), (f32x4){0.f, 0.f, 0.f, 0.f}, 0, 0, 0);
;           }
; #pragma unroll
;           for (int ks = 1; ks < NKS; ++ks) {
;             const bf16x8 kf = *(const bf16x8*)(Ks + (t * 16 + fr) * KST + ks * 32 + fq * 8);
; #pragma unroll
;             for (int qq = 0; qq < QG; ++qq) S[qq][t] = mfma16(kf, *(const bf16x8*)(Qs2 + ((q0 + qq) * NKS + ks) * 512), S[qq][t]);
;           }
;         }
.LBB0_561:
	s_lshl_b32 s4, s15, 1
	s_add_i32 s4, s4, 2
	v_lshlrev_b32_e32 v34, 1, v0
	v_lshlrev_b32_e32 v38, 1, v106
	v_lshlrev_b32_e32 v42, 1, v108
	v_lshl_add_u32 v50, v136, 1, s4
	v_lshl_add_u32 v46, v138, 1, s4
	global_load_dwordx4 v[34:37], v34, s[0:1]
	global_load_dwordx4 v[38:41], v38, s[0:1]
	global_load_dwordx4 v[42:45], v42, s[0:1]
	global_load_dwordx4 v[50:53], v50, s[2:3]
	global_load_dwordx4 v[46:49], v46, s[2:3]
	v_cmp_le_i32_e32 vcc, s17, v171
	s_and_saveexec_b64 s[12:13], vcc
	s_cbranch_execz .LBB0_560
	ds_read_b128 v[56:59], v86
	ds_read_b128 v[114:117], v86 offset:1024
	ds_read_b128 v[68:71], v86 offset:3072
	ds_read_b128 v[144:147], v86 offset:2048
	ds_read_b128 v[60:63], v157
	ds_read_b128 v[140:143], v157 offset:64
	ds_read_b128 v[72:75], v158
	ds_read_b128 v[80:83], v159
	ds_read_b128 v[118:121], v160
	s_waitcnt lgkmcnt(0)
	v_mfma_f32_16x16x32_bf16 v[64:67], v[60:63], v[56:59], 0
	v_cmp_le_i32_e32 vcc, s15, v170
	v_mfma_f32_16x16x32_bf16 v[60:63], v[60:63], v[68:71], 0
	v_mfma_f32_16x16x32_bf16 v[76:79], v[72:75], v[56:59], 0
	v_mfma_f32_16x16x32_bf16 v[72:75], v[72:75], v[68:71], 0
	v_mfma_f32_16x16x32_bf16 v[110:113], v[80:83], v[56:59], 0
	v_mfma_f32_16x16x32_bf16 v[80:83], v[80:83], v[68:71], 0
	v_mfma_f32_16x16x32_bf16 v[56:59], v[118:121], v[56:59], 0
	v_mfma_f32_16x16x32_bf16 v[68:71], v[118:121], v[68:71], 0
	ds_read_b128 v[118:121], v86 offset:4096
	s_nop 0
	ds_read_b128 v[148:151], v86 offset:5120
	v_mfma_f32_16x16x32_bf16 v[64:67], v[140:143], v[114:117], v[64:67]
	s_waitcnt lgkmcnt(0)
	v_mfma_f32_16x16x32_bf16 v[60:63], v[140:143], v[118:121], v[60:63]
	ds_read_b128 v[140:143], v158 offset:64
	s_waitcnt lgkmcnt(0)
	v_mfma_f32_16x16x32_bf16 v[76:79], v[140:143], v[114:117], v[76:79]
	v_mfma_f32_16x16x32_bf16 v[140:143], v[140:143], v[118:121], v[72:75]
	s_nop 2
	ds_read_b128 v[72:75], v159 offset:64
	s_waitcnt lgkmcnt(0)
	v_mfma_f32_16x16x32_bf16 v[110:113], v[72:75], v[114:117], v[110:113]
	v_mfma_f32_16x16x32_bf16 v[82:85], v[72:75], v[118:121], v[80:83]
	ds_read_b128 v[72:75], v160 offset:64
	s_waitcnt lgkmcnt(0)
	v_mfma_f32_16x16x32_bf16 v[114:117], v[72:75], v[114:117], v[56:59]
	s_nop 2
	ds_read_b128 v[54:57], v157 offset:128
	v_mfma_f32_16x16x32_bf16 v[118:121], v[72:75], v[118:121], v[68:71]
	s_waitcnt lgkmcnt(0)
	v_mfma_f32_16x16x32_bf16 v[70:73], v[54:57], v[144:147], v[64:67]
	v_mfma_f32_16x16x32_bf16 v[58:61], v[54:57], v[148:151], v[60:63]
	ds_read_b128 v[54:57], v158 offset:128
	s_nop 1
	ds_read_b128 v[62:65], v159 offset:128
	s_waitcnt lgkmcnt(1)
	v_mfma_f32_16x16x32_bf16 v[66:69], v[54:57], v[144:147], v[76:79]
	s_nop 2
	ds_read_b128 v[74:77], v160 offset:128
	v_mfma_f32_16x16x32_bf16 v[54:57], v[54:57], v[148:151], v[140:143]
	s_waitcnt lgkmcnt(1)
	v_mfma_f32_16x16x32_bf16 v[78:81], v[62:65], v[144:147], v[110:113]
	v_mfma_f32_16x16x32_bf16 v[62:65], v[62:65], v[148:151], v[82:85]
	s_waitcnt lgkmcnt(0)
	v_mfma_f32_16x16x32_bf16 v[82:85], v[74:77], v[144:147], v[114:117]
	v_mfma_f32_16x16x32_bf16 v[74:77], v[74:77], v[148:151], v[118:121]
	s_and_saveexec_b64 s[4:5], vcc
	s_xor_b64 s[4:5], exec, s[4:5]
	s_cbranch_execz .LBB0_564
	v_max3_f32 v107, v70, v71, v72
	s_mov_b32 s6, 0x3e16c740
	v_max3_f32 v107, v107, v73, v66
	v_max3_f32 v107, v107, v67, v68
	v_max3_f32 v107, v107, v69, v78
	v_max3_f32 v107, v107, v79, v80
	v_max3_f32 v107, v107, v81, v82
	v_max3_f32 v107, v107, v83, v84
	v_max3_f32 v107, v107, v85, v107
	v_mov_b32_e32 v109, v107
	s_nop 1
	v_permlane16_swap_b32_e32 v107, v109
	v_max3_f32 v107, v107, v109, v109
	v_mov_b32_e32 v109, v107
	s_nop 1
	v_permlane32_swap_b32_e32 v107, v109
	v_max3_f32 v107, v107, v109, v109
	v_fma_f32 v107, v107, s6, 0
	v_max3_f32 v107, v169, v107, v169
	v_sub_f32_e32 v116, 0, v107
	v_pk_fma_f32 v[118:119], v[84:85], s[6:7], v[116:117] op_sel_hi:[1,0,0]
	v_pk_fma_f32 v[120:121], v[82:83], s[6:7], v[116:117] op_sel_hi:[1,0,0]
	v_pk_fma_f32 v[140:141], v[80:81], s[6:7], v[116:117] op_sel_hi:[1,0,0]
	v_pk_fma_f32 v[110:111], v[78:79], s[6:7], v[116:117] op_sel_hi:[1,0,0]
	v_pk_fma_f32 v[114:115], v[68:69], s[6:7], v[116:117] op_sel_hi:[1,0,0]
	v_pk_fma_f32 v[142:143], v[66:67], s[6:7], v[116:117] op_sel_hi:[1,0,0]
	v_pk_fma_f32 v[112:113], v[72:73], s[6:7], v[116:117] op_sel_hi:[1,0,0]
	v_pk_fma_f32 v[116:117], v[70:71], s[6:7], v[116:117] op_sel_hi:[1,0,0]
